# loop-edge edit: attention KV loop head branches on SCC directly (one scalar op fewer per step), on top of the conv-pass warm-up version
# baseline (speedup 1.0000x reference)
.LBB0_740:
	s_add_i32 s26, s48, 3
	s_cmp_ge_u32 s26, s46
	s_cselect_b64 s[2:3], -1, 0
	s_cbranch_scc1 .LBB0_743
	s_and_b32 s26, s26, 3
	s_mulk_i32 s26, 0x5800
	s_add_i32 s26, s45, s26
	s_mov_b32 m0, s26
	s_andn2_b64 vcc, exec, s[24:25]
	global_load_lds_dwordx4 v[152:153], off
	s_add_i32 m0, s26, 0x2000
	s_nop 0
	global_load_lds_dwordx4 v[150:151], off
	s_cbranch_vccnz .LBB0_743
	s_add_i32 m0, s26, 0x4000
	s_nop 0
	global_load_lds_dwordx4 v[148:149], off
